# grid barrier: non-leader blocks poll the global release word (TOPGEN) directly instead of waiting for their XCD leader to forward it through the per-XCD generation word (one fewer atomic->poll hop), o
# speedup vs baseline: 1.0163x; 1.0002x over previous
; __device__ __forceinline__ unsigned xb_ld(unsigned* p)              { return __hip_atomic_load(p, __ATOMIC_RELAXED, __HIP_MEMORY_SCOPE_AGENT); }
; __device__ __forceinline__ unsigned xb_add(unsigned* p, unsigned v) { return __hip_atomic_fetch_add(p, v, __ATOMIC_RELAXED, __HIP_MEMORY_SCOPE_AGENT); }
; #define XB_SPIN(cond, bar) do { unsigned _sp = 0; while (cond) { __builtin_amdgcn_s_sleep(1); \
;     if ((++_sp & 255u) == 0u) { if (xb_ld(&(bar)[XB_TMO])) break; if (_sp > XB_SPIN_CAP) { atomicAdd(&(bar)[XB_TMO], 1u); break; } } } } while (0)
; __device__ __forceinline__ void xcd_barrier(const XcdBarrier& b) {
;     ...
;         const unsigned old = xb_add(&bar[XB_XSUB(b.x)], 1u);
;         const unsigned gen = old / nloc;
;         if (old + 1u == (gen + 1u) * nloc) {
;             __builtin_amdgcn_fence(__ATOMIC_RELEASE, "agent");
;             asm volatile("s_waitcnt vmcnt(0)" ::: "memory");
;             const unsigned og = xb_add(&bar[XB_TOP], 1u);
;             const unsigned tg = og / nx;
;             if (og + 1u == (tg + 1u) * nx) xb_add(&bar[XB_TOPGEN], 1u);
;             else XB_SPIN(xb_ld(&bar[XB_TOPGEN]) == tg, bar);
;             __builtin_amdgcn_fence(__ATOMIC_ACQUIRE, "agent");
;             xb_add(&bar[XB_XGEN(b.x)], 1u);
;             asm volatile("s_waitcnt vmcnt(0)" ::: "memory");
;         } else {
;             XB_SPIN(xb_ld(&bar[XB_XGEN(b.x)]) == gen, bar);
.LBB0_809:
	s_or_b64 exec, exec, s[40:41]
	v_cvt_f32_u32_e32 v9, v3
	s_waitcnt vmcnt(0)
	v_readfirstlane_b32 s15, v8
	v_sub_u32_e32 v8, 0, v3
	v_rcp_iflag_f32_e32 v9, v9
	v_add_u32_e32 v10, s15, v0
	v_mul_f32_e32 v9, 0x4f7ffffe, v9
	v_cvt_u32_f32_e32 v9, v9
	v_mul_lo_u32 v0, v8, v9
	v_mul_hi_u32 v0, v9, v0
	v_add_u32_e32 v0, v9, v0
	v_mul_hi_u32 v0, v10, v0
	v_mul_lo_u32 v8, v0, v3
	v_sub_u32_e32 v8, v10, v8
	v_add_u32_e32 v9, 1, v0
	v_cmp_ge_u32_e32 vcc, v8, v3
	s_nop 1
	v_cndmask_b32_e32 v0, v0, v9, vcc
	v_sub_u32_e32 v9, v8, v3
	v_cndmask_b32_e32 v8, v8, v9, vcc
	v_add_u32_e32 v9, 1, v0
	v_cmp_ge_u32_e32 vcc, v8, v3
	v_add_u32_e32 v8, 1, v10
	s_nop 0
	v_cndmask_b32_e32 v0, v0, v9, vcc
	v_mul_lo_u32 v9, v3, v0
	v_add_u32_e32 v3, v9, v3
	v_cmp_ne_u32_e32 vcc, v8, v3
	s_and_saveexec_b64 s[24:25], vcc
	s_xor_b64 s[40:41], exec, s[24:25]
	s_cbranch_execz .LBB0_823
	v_readlane_b32 s24, v253, 61
	v_readlane_b32 s25, v253, 62
	s_waitcnt lgkmcnt(0)
	s_nop 3
	buffer_inv sc1
	global_load_dword v2, v1, s[24:25] sc1
	s_waitcnt vmcnt(0)
	v_cmp_eq_u32_e32 vcc, v2, v0
	s_and_saveexec_b64 s[42:43], vcc
	s_cbranch_execz .LBB0_822
	s_mov_b32 s15, 1
	s_mov_b64 s[44:45], 0
	s_branch .LBB0_813
